# adds: attention O epilogue lane^1 exchange by DPP quad_perm instead of 64 ds_bpermute + lgkmcnt(0) per block
# baseline (speedup 1.0000x reference)
; #define SBAR() __builtin_amdgcn_sched_barrier(0)
; #define RD8(S, d0) do { constexpr int b_ = v_rd_off(d0, 0, 0); TRRD(S##l0, b_); TRRD(S##h0, b_ + 2048); TRRD(S##l1, b_ + 4096); TRRD(S##h1, b_ + 6144); \
;         TRRD(S##l2, b_ + 8192); TRRD(S##h2, b_ + 10240); TRRD(S##l3, b_ + 12288); TRRD(S##h3, b_ + 14336); } while (0)
; #define RD8(S, d0) do { constexpr int b_ = v_rd_off(d0, 0, 0); TRRD(S##l0, b_); TRRD(S##h0, b_ + 2048); TRRD(S##l1, b_ + 4096); TRRD(S##h1, b_ + 6144); \
;         TRRD(S##l2, b_ + 8192); TRRD(S##h2, b_ + 10240); TRRD(S##l3, b_ + 12288); TRRD(S##h3, b_ + 14336); } while (0)
; __device__ __forceinline__ void finishSM(f32x16& p0, f32x16& p1, float alpha, float& l_reg, bf16x8& pa0, bf16x8& pa1, bf16x8& pa2, bf16x8& pa3) {
;     for (int r = 0; r < 16; ++r) p1[r] = __builtin_amdgcn_exp2f(p1[r]);
;     float ps = 0; for (int r = 0; r < 16; ++r) ps += p0[r]; for (int r = 0; r < 16; ++r) ps += p1[r];
;     { auto rr = __builtin_amdgcn_permlane32_swap(__float_as_uint(ps), __float_as_uint(ps), false, false);
;       ps = __uint_as_float(rr[0]) + __uint_as_float(rr[1]); }
;     l_reg = l_reg * alpha + ps;
;     ...
;     PK4(p0, 0, pa0); PK4(p0, 8, pa1); PK4(p1, 0, pa2); PK4(p1, 8, pa3);
; __device__ __forceinline__ void pv_part(f32x16* o, int vb, bf16x8 pa0, bf16x8 pa1, bf16x8 pa2, bf16x8 pa3, f32x16& x0, f32x16& x1, float& m_reg, float& mn, float& alpha) {
;     ...
;     const float mnL = -mn * C2;
;     SBAR();
;     RD8(B, 3);
;     asm volatile("s_waitcnt lgkmcnt(8)" ::: "memory"); SBAR(); MM4(A, 2);
; #pragma unroll
;     for (int r = 0; r < 16; ++r) x0[r] = fmaf(x0[r], C2, mnL);
; #pragma unroll
;     for (int r = 0; r < 16; ++r) x1[r] = fmaf(x1[r], C2, mnL);
; #pragma unroll
;     for (int r = 0; r < 6; ++r) x0[r] = __builtin_amdgcn_exp2f(x0[r]);
;     SBAR();
;     asm volatile("s_waitcnt lgkmcnt(0)" ::: "memory"); SBAR(); MM4(B, 3);
; #pragma unroll
;     for (int r = 6; r < 16; ++r) x0[r] = __builtin_amdgcn_exp2f(x0[r]);
.LBB0_575:
	v_cndmask_b32_e64 v96, v115, v189, s[4:5]
	v_mul_f32_e32 v96, 0xbdd53b94, v96
	v_fmamk_f32 v80, v80, 0x3dd53b94, v96
	v_fmamk_f32 v81, v81, 0x3dd53b94, v96
	v_fmamk_f32 v82, v82, 0x3dd53b94, v96
	v_fmamk_f32 v83, v83, 0x3dd53b94, v96
	v_fmamk_f32 v84, v84, 0x3dd53b94, v96
	v_fmamk_f32 v85, v85, 0x3dd53b94, v96
	v_fmamk_f32 v86, v86, 0x3dd53b94, v96
	v_fmamk_f32 v87, v87, 0x3dd53b94, v96
	v_fmamk_f32 v88, v88, 0x3dd53b94, v96
	v_fmamk_f32 v89, v89, 0x3dd53b94, v96
	v_fmamk_f32 v90, v90, 0x3dd53b94, v96
	v_fmamk_f32 v91, v91, 0x3dd53b94, v96
	v_fmamk_f32 v92, v92, 0x3dd53b94, v96
	v_fmamk_f32 v93, v93, 0x3dd53b94, v96
	v_fmamk_f32 v94, v94, 0x3dd53b94, v96
	v_fmamk_f32 v95, v95, 0x3dd53b94, v96
	v_fmamk_f32 v64, v64, 0x3dd53b94, v96
	v_fmamk_f32 v65, v65, 0x3dd53b94, v96
	v_fmamk_f32 v66, v66, 0x3dd53b94, v96
	v_fmamk_f32 v67, v67, 0x3dd53b94, v96
	v_fmamk_f32 v68, v68, 0x3dd53b94, v96
	v_fmamk_f32 v69, v69, 0x3dd53b94, v96
	v_fmamk_f32 v70, v70, 0x3dd53b94, v96
	v_fmamk_f32 v71, v71, 0x3dd53b94, v96
	v_fmamk_f32 v72, v72, 0x3dd53b94, v96
	v_fmamk_f32 v73, v73, 0x3dd53b94, v96
	v_fmamk_f32 v74, v74, 0x3dd53b94, v96
	v_fmamk_f32 v75, v75, 0x3dd53b94, v96
	v_fmamk_f32 v76, v76, 0x3dd53b94, v96
	v_fmamk_f32 v77, v77, 0x3dd53b94, v96
	v_fmamk_f32 v78, v78, 0x3dd53b94, v96
	v_fmac_f32_e32 v96, 0x3dd53b94, v79
	v_exp_f32_e32 v79, v80
	v_exp_f32_e32 v80, v81
	v_exp_f32_e32 v81, v82
	v_exp_f32_e32 v82, v83
	v_exp_f32_e32 v83, v84
	v_exp_f32_e32 v84, v85
	v_exp_f32_e32 v85, v86
	v_exp_f32_e32 v86, v87
	v_exp_f32_e32 v87, v88
	v_exp_f32_e32 v88, v89
	v_exp_f32_e32 v89, v90
	v_exp_f32_e32 v90, v91
	v_exp_f32_e32 v91, v92
	v_exp_f32_e32 v92, v93
	v_exp_f32_e32 v93, v94
	v_exp_f32_e32 v94, v95
	v_exp_f32_e32 v95, v64
	v_add_f32_e32 v64, 0, v79
	v_add_f32_e32 v64, v80, v64
	v_add_f32_e32 v64, v81, v64
	v_add_f32_e32 v64, v82, v64
	v_add_f32_e32 v64, v83, v64
	v_add_f32_e32 v64, v84, v64
	v_add_f32_e32 v64, v85, v64
	v_add_f32_e32 v64, v86, v64
	v_add_f32_e32 v64, v87, v64
	v_add_f32_e32 v64, v88, v64
	v_add_f32_e32 v64, v89, v64
	v_add_f32_e32 v64, v90, v64
	v_add_f32_e32 v64, v91, v64
	v_exp_f32_e32 v97, v65
	v_add_f32_e32 v64, v92, v64
	v_exp_f32_e32 v98, v66
	v_add_f32_e32 v64, v93, v64
	v_exp_f32_e32 v99, v67
	v_add_f32_e32 v64, v94, v64
	v_exp_f32_e32 v100, v68
	v_add_f32_e32 v64, v95, v64
	v_exp_f32_e32 v101, v69
	v_add_f32_e32 v64, v97, v64
	v_exp_f32_e32 v102, v70
	v_add_f32_e32 v64, v98, v64
	v_exp_f32_e32 v103, v71
	v_add_f32_e32 v64, v99, v64
	v_exp_f32_e32 v104, v72
	v_add_f32_e32 v64, v100, v64
	v_exp_f32_e32 v105, v73
	v_add_f32_e32 v64, v101, v64
	v_exp_f32_e32 v106, v74
	v_add_f32_e32 v64, v102, v64
	v_exp_f32_e32 v107, v75
	v_add_f32_e32 v64, v103, v64
	v_exp_f32_e32 v108, v76
	v_add_f32_e32 v64, v104, v64
	v_exp_f32_e32 v109, v77
	v_add_f32_e32 v64, v105, v64
	v_exp_f32_e32 v110, v78
	v_add_f32_e32 v64, v106, v64
	v_exp_f32_e32 v96, v96
	v_add_f32_e32 v64, v107, v64
	v_add_f32_e32 v64, v108, v64
	v_add_f32_e32 v64, v109, v64
	v_add_f32_e32 v64, v110, v64
	v_add_f32_e32 v64, v96, v64
	v_mov_b32_e32 v65, v64
	s_nop 1
	v_permlane32_swap_b32_e32 v64, v65
	v_cvt_pk_bf16_f32 v66, v79, v80
	v_cvt_pk_bf16_f32 v67, v81, v82
	v_cvt_pk_bf16_f32 v68, v83, v84
	v_cvt_pk_bf16_f32 v69, v85, v86
	v_cvt_pk_bf16_f32 v70, v87, v88
	v_cvt_pk_bf16_f32 v71, v89, v90
	v_cvt_pk_bf16_f32 v72, v91, v92
	v_cvt_pk_bf16_f32 v73, v93, v94
	v_cvt_pk_bf16_f32 v74, v95, v97
	v_cvt_pk_bf16_f32 v75, v98, v99
	v_cvt_pk_bf16_f32 v76, v100, v101
	v_cvt_pk_bf16_f32 v77, v102, v103
	v_cvt_pk_bf16_f32 v78, v104, v105
	v_cvt_pk_bf16_f32 v79, v106, v107
	v_cvt_pk_bf16_f32 v80, v108, v109
	v_cvt_pk_bf16_f32 v81, v110, v96
	s_nop 0
	v_permlane32_swap_b32_e32 v66, v68
	v_permlane32_swap_b32_e32 v67, v69
	v_permlane32_swap_b32_e32 v70, v72
	v_permlane32_swap_b32_e32 v71, v73
	v_permlane32_swap_b32_e32 v74, v76
	v_permlane32_swap_b32_e32 v75, v77
	v_permlane32_swap_b32_e32 v78, v80
	v_permlane32_swap_b32_e32 v79, v81
	ds_read_b64_tr_b16 v[82:83], v182 offset:0
	ds_read_b64_tr_b16 v[84:85], v182 offset:0x800
	ds_read_b64_tr_b16 v[86:87], v182 offset:0x1000
	ds_read_b64_tr_b16 v[88:89], v182 offset:0x1800
	ds_read_b64_tr_b16 v[90:91], v182 offset:0x2000
	ds_read_b64_tr_b16 v[92:93], v182 offset:0x2800
	ds_read_b64_tr_b16 v[94:95], v182 offset:0x3000
	ds_read_b64_tr_b16 v[96:97], v182 offset:0x3800
	ds_read_b64_tr_b16 v[98:99], v182 offset:0x200
	ds_read_b64_tr_b16 v[100:101], v182 offset:0xa00
	ds_read_b64_tr_b16 v[102:103], v182 offset:0x1200
	ds_read_b64_tr_b16 v[104:105], v182 offset:0x1a00
	ds_read_b64_tr_b16 v[106:107], v182 offset:0x2200
	ds_read_b64_tr_b16 v[108:109], v182 offset:0x2a00
	ds_read_b64_tr_b16 v[116:117], v182 offset:0x3200
	ds_read_b64_tr_b16 v[118:119], v182 offset:0x3a00
	s_waitcnt lgkmcnt(8)
	s_nop 0
	v_mfma_f32_32x32x16_bf16 v[32:47], v[66:69], v[82:85], v[32:47]
	v_mfma_f32_32x32x16_bf16 v[32:47], v[70:73], v[86:89], v[32:47]
	v_mfma_f32_32x32x16_bf16 v[32:47], v[74:77], v[90:93], v[32:47]
	v_mfma_f32_32x32x16_bf16 v[32:47], v[78:81], v[94:97], v[32:47]
	ds_read_b64_tr_b16 v[82:83], v182 offset:0x400
	ds_read_b64_tr_b16 v[84:85], v182 offset:0xc00
	ds_read_b64_tr_b16 v[86:87], v182 offset:0x1400
	ds_read_b64_tr_b16 v[88:89], v182 offset:0x1c00
	ds_read_b64_tr_b16 v[90:91], v182 offset:0x2400
	ds_read_b64_tr_b16 v[92:93], v182 offset:0x2c00
	ds_read_b64_tr_b16 v[94:95], v182 offset:0x3400
	ds_read_b64_tr_b16 v[96:97], v182 offset:0x3c00
	s_waitcnt lgkmcnt(8)
; #define SBAR() __builtin_amdgcn_sched_barrier(0)
; __device__ __forceinline__ int crow(int r, int hi) { return (r & 3) + 8 * (r >> 2) + 4 * hi; }
; __device__ __forceinline__ unsigned cvtpk(float lo, float hi) { unsigned r; asm volatile("v_cvt_pk_bf16_f32 %0, %1, %2" : "=v"(r) : "v"(lo), "v"(hi)); return r; }
; #define RD8(S, d0) do { constexpr int b_ = v_rd_off(d0, 0, 0); TRRD(S##l0, b_); TRRD(S##h0, b_ + 2048); TRRD(S##l1, b_ + 4096); TRRD(S##h1, b_ + 6144); \
;         TRRD(S##l2, b_ + 8192); TRRD(S##h2, b_ + 10240); TRRD(S##l3, b_ + 12288); TRRD(S##h3, b_ + 14336); } while (0)
; #define RD8(S, d0) do { constexpr int b_ = v_rd_off(d0, 0, 0); TRRD(S##l0, b_); TRRD(S##h0, b_ + 2048); TRRD(S##l1, b_ + 4096); TRRD(S##h1, b_ + 6144); \
;         TRRD(S##l2, b_ + 8192); TRRD(S##h2, b_ + 10240); TRRD(S##l3, b_ + 12288); TRRD(S##h3, b_ + 14336); } while (0)
; __device__ __forceinline__ int crow(int r, int hi) { return (r & 3) + 8 * (r >> 2) + 4 * hi; }
; __device__ __forceinline__ void pv_tile(f32x16* o, int vb, bf16x8 pa0, bf16x8 pa1, bf16x8 pa2, bf16x8 pa3) {
;     ...
;     RD8(A, 2);
;     asm volatile("s_waitcnt lgkmcnt(8)" ::: "memory"); SBAR(); MM4(B, 1); SBAR();
;     RD8(B, 3);
;     asm volatile("s_waitcnt lgkmcnt(8)" ::: "memory"); SBAR(); MM4(A, 2); SBAR();
;     asm volatile("s_waitcnt lgkmcnt(0)" ::: "memory"); SBAR(); MM4(B, 3);
; __device__ __forceinline__ void attn_block(const BlockRef& cur, char* lds) {
;     ...
;     if (hi == 0) li_l[r32] = l_reg; asm volatile("s_waitcnt lgkmcnt(0)" ::: "memory");
;     float rli[16];
; #pragma unroll
;     for (int r = 0; r < 16; ++r) rli[r] = __builtin_amdgcn_rcpf(li_l[crow(r, hi)]);
;     bf16* Ow = cur.O + (size_t)(wid * QBLK) * LDO;
; #pragma unroll
;     for (int r = 0; r < 16; ++r) { const int orow = crow(r, hi);
; #pragma unroll
;         for (int d0 = 0; d0 < 4; ++d0) { const float v = o[d0][r] * rli[r];
;             const float vn = __shfl_xor(v, 1);
;             if ((r32 & 1) == 0) *(unsigned*)(Ow + (size_t)orow * LDO + d0 * 32 + r32) = cvtpk(v, vn); } }
	v_mfma_f32_32x32x16_bf16 v[48:63], v[66:69], v[98:101], v[48:63]
	v_mfma_f32_32x32x16_bf16 v[48:63], v[70:73], v[102:105], v[48:63]
	v_mfma_f32_32x32x16_bf16 v[48:63], v[74:77], v[106:109], v[48:63]
	v_mfma_f32_32x32x16_bf16 v[48:63], v[78:81], v[116:119], v[48:63]
	ds_read_b64_tr_b16 v[98:99], v182 offset:0x600
	ds_read_b64_tr_b16 v[100:101], v182 offset:0xe00
	ds_read_b64_tr_b16 v[102:103], v182 offset:0x1600
	ds_read_b64_tr_b16 v[104:105], v182 offset:0x1e00
	ds_read_b64_tr_b16 v[106:107], v182 offset:0x2600
	ds_read_b64_tr_b16 v[108:109], v182 offset:0x2e00
	ds_read_b64_tr_b16 v[116:117], v182 offset:0x3600
	ds_read_b64_tr_b16 v[118:119], v182 offset:0x3e00
	s_waitcnt lgkmcnt(8)
	v_mfma_f32_32x32x16_bf16 v[16:31], v[66:69], v[82:85], v[16:31]
	v_mfma_f32_32x32x16_bf16 v[16:31], v[70:73], v[86:89], v[16:31]
	v_mfma_f32_32x32x16_bf16 v[16:31], v[74:77], v[90:93], v[16:31]
	v_mfma_f32_32x32x16_bf16 v[16:31], v[78:81], v[94:97], v[16:31]
	s_waitcnt lgkmcnt(0)
	v_mfma_f32_32x32x16_bf16 v[0:15], v[66:69], v[98:101], v[0:15]
	v_mfma_f32_32x32x16_bf16 v[0:15], v[70:73], v[102:105], v[0:15]
	v_mfma_f32_32x32x16_bf16 v[0:15], v[74:77], v[106:109], v[0:15]
	v_mfma_f32_32x32x16_bf16 v[0:15], v[78:81], v[116:119], v[0:15]
	s_and_saveexec_b64 s[2:3], s[0:1]
	v_add_f32_e32 v66, v112, v113
	v_fmac_f32_e32 v66, v179, v172
	v_add_f32_e32 v64, v64, v65
	v_fmac_f32_e32 v64, v66, v114
	ds_write_b32 v178, v64
	s_or_b64 exec, exec, s[2:3]
	v_readlane_b32 s0, v255, 7
	v_readlane_b32 s1, v255, 8
	s_ashr_i32 s0, s0, 2
	s_waitcnt lgkmcnt(0)
	s_ashr_i32 s1, s0, 31
	ds_read_b128 v[76:79], v174
	ds_read_b128 v[72:75], v174 offset:32
	s_lshl_b64 s[0:1], s[0:1], 24
	s_add_u32 s2, s8, s0
	s_addc_u32 s72, s9, s1
	s_lshl_b32 s0, s10, 19
	v_writelane_b32 v255, s2, 19
	s_add_u32 s0, s2, s0
	v_readlane_b32 s2, v253, 5
	s_waitcnt lgkmcnt(1)
	v_rcp_f32_e32 v76, v76
	s_addc_u32 s1, s72, 0
	s_lshl_b32 s73, s2, 1
	v_xor_b32_e32 v80, 1, v191
	s_add_u32 s2, s0, s73
	v_cmp_lt_i32_e32 vcc, v80, v192
	s_addc_u32 s3, s1, 0
	s_ashr_i32 s13, s12, 31
	v_cndmask_b32_e32 v80, v191, v80, vcc
	ds_read_b128 v[68:71], v174 offset:64
	ds_read_b128 v[64:67], v174 offset:96
	s_lshl_b64 s[0:1], s[12:13], 11
	v_lshlrev_b32_e32 v174, 2, v80
	v_mul_f32_e32 v32, v32, v76
	s_add_u32 s2, s2, s0
	s_nop 1
	v_mov_b32_dpp v84, v32 quad_perm:[1,0,3,2] row_mask:0xf bank_mask:0xf
	s_addc_u32 s3, s3, s1
	v_and_b32_e32 v80, 1, v175
	v_lshlrev_b32_e32 v160, 1, v177
	v_cmp_eq_u32_e64 s[0:1], 0, v80
	v_lshl_add_u64 v[80:81], s[2:3], 0, v[160:161]
	v_lshlrev_b32_e32 v160, 13, v176
	v_lshl_add_u64 v[82:83], v[80:81], 0, v[160:161]
	s_mov_b64 s[2:3], 0x400
	v_lshl_add_u64 v[80:81], v[82:83], 0, s[2:3]
	s_and_saveexec_b64 s[2:3], s[0:1]
	s_cbranch_execz .LBB0_579
	s_waitcnt lgkmcnt(0)
	v_cvt_pk_bf16_f32 v32, v32, v84
	global_store_dword v[80:81], v32, off
.LBB0_579:
	s_or_b64 exec, exec, s[2:3]
	v_mul_f32_e32 v32, v48, v76
	s_nop 1
	v_mov_b32_dpp v48, v32 quad_perm:[1,0,3,2] row_mask:0xf bank_mask:0xf
	s_and_saveexec_b64 s[2:3], s[0:1]
	s_cbranch_execz .LBB0_581
	s_waitcnt lgkmcnt(0)
	v_cvt_pk_bf16_f32 v32, v32, v48
	global_store_dword v[82:83], v32, off offset:1088
.LBB0_581:
	s_or_b64 exec, exec, s[2:3]
	v_mul_f32_e32 v16, v16, v76
	s_nop 1
	v_mov_b32_dpp v32, v16 quad_perm:[1,0,3,2] row_mask:0xf bank_mask:0xf
	s_and_saveexec_b64 s[2:3], s[0:1]
	s_cbranch_execz .LBB0_583
	s_waitcnt lgkmcnt(0)
	v_cvt_pk_bf16_f32 v16, v16, v32
	global_store_dword v[82:83], v16, off offset:1152
.LBB0_583:
	s_or_b64 exec, exec, s[2:3]
	v_mul_f32_e32 v0, v0, v76
	s_nop 1
	v_mov_b32_dpp v16, v0 quad_perm:[1,0,3,2] row_mask:0xf bank_mask:0xf
	s_and_saveexec_b64 s[2:3], s[0:1]
	s_cbranch_execz .LBB0_585
	s_waitcnt lgkmcnt(0)
	v_cvt_pk_bf16_f32 v0, v0, v16
	global_store_dword v[82:83], v0, off offset:1216
.LBB0_585:
	s_or_b64 exec, exec, s[2:3]
	v_rcp_f32_e32 v0, v77
	s_waitcnt lgkmcnt(0)
	v_mul_f32_e32 v16, v33, v0
	s_nop 1
	v_mov_b32_dpp v32, v16 quad_perm:[1,0,3,2] row_mask:0xf bank_mask:0xf
	s_and_saveexec_b64 s[2:3], s[0:1]
	s_cbranch_execz .LBB0_587
	s_waitcnt lgkmcnt(0)
	v_cvt_pk_bf16_f32 v16, v16, v32
	global_store_dword v[82:83], v16, off offset:3072
.LBB0_587:
	s_or_b64 exec, exec, s[2:3]
	v_mul_f32_e32 v16, v49, v0
	s_waitcnt lgkmcnt(0)
	s_nop 1
	v_mov_b32_dpp v32, v16 quad_perm:[1,0,3,2] row_mask:0xf bank_mask:0xf
	s_and_saveexec_b64 s[2:3], s[0:1]
	s_cbranch_execz .LBB0_589
	s_waitcnt lgkmcnt(0)
	v_cvt_pk_bf16_f32 v16, v16, v32
	global_store_dword v[82:83], v16, off offset:3136
.LBB0_589:
	s_or_b64 exec, exec, s[2:3]
	v_mul_f32_e32 v16, v17, v0
	s_nop 1
	v_mov_b32_dpp v17, v16 quad_perm:[1,0,3,2] row_mask:0xf bank_mask:0xf
	s_and_saveexec_b64 s[2:3], s[0:1]
	s_cbranch_execz .LBB0_591
	s_waitcnt lgkmcnt(0)
	v_cvt_pk_bf16_f32 v16, v16, v17
	global_store_dword v[82:83], v16, off offset:3200
.LBB0_591:
	s_or_b64 exec, exec, s[2:3]
	v_mul_f32_e32 v0, v1, v0
	s_nop 1
	v_mov_b32_dpp v1, v0 quad_perm:[1,0,3,2] row_mask:0xf bank_mask:0xf
	s_and_saveexec_b64 s[2:3], s[0:1]
	s_cbranch_execz .LBB0_593
	s_waitcnt lgkmcnt(0)
	v_cvt_pk_bf16_f32 v0, v0, v1
	global_store_dword v[82:83], v0, off offset:3264
.LBB0_593:
	s_or_b64 exec, exec, s[2:3]
	v_rcp_f32_e32 v0, v78
	s_waitcnt lgkmcnt(0)
	v_mul_f32_e32 v1, v34, v0
	s_nop 1
	v_mov_b32_dpp v16, v1 quad_perm:[1,0,3,2] row_mask:0xf bank_mask:0xf
	s_and_saveexec_b64 s[2:3], s[0:1]
	s_cbranch_execz .LBB0_595
	s_waitcnt lgkmcnt(0)
	v_cvt_pk_bf16_f32 v1, v1, v16
	v_add_co_u32_e32 v16, vcc, 0x1000, v80
	s_nop 1
	v_addc_co_u32_e32 v17, vcc, 0, v81, vcc
	global_store_dword v[16:17], v1, off
; __device__ __forceinline__ int crow(int r, int hi) { return (r & 3) + 8 * (r >> 2) + 4 * hi; }
; __device__ __forceinline__ unsigned cvtpk(float lo, float hi) { unsigned r; asm volatile("v_cvt_pk_bf16_f32 %0, %1, %2" : "=v"(r) : "v"(lo), "v"(hi)); return r; }
; __device__ __forceinline__ int crow(int r, int hi) { return (r & 3) + 8 * (r >> 2) + 4 * hi; }
; __device__ __forceinline__ void attn_block(const BlockRef& cur, char* lds) {
;     ...
;     for (int r = 0; r < 16; ++r) { const int orow = crow(r, hi);
; #pragma unroll
;         for (int d0 = 0; d0 < 4; ++d0) { const float v = o[d0][r] * rli[r];
;             const float vn = __shfl_xor(v, 1);
;             if ((r32 & 1) == 0) *(unsigned*)(Ow + (size_t)orow * LDO + d0 * 32 + r32) = cvtpk(v, vn); } }
.LBB0_595:
	s_or_b64 exec, exec, s[2:3]
	v_mul_f32_e32 v1, v50, v0
	s_waitcnt lgkmcnt(0)
	s_nop 1
	v_mov_b32_dpp v16, v1 quad_perm:[1,0,3,2] row_mask:0xf bank_mask:0xf
	s_and_saveexec_b64 s[2:3], s[0:1]
	s_cbranch_execz .LBB0_597
	s_waitcnt lgkmcnt(0)
	v_cvt_pk_bf16_f32 v1, v1, v16
	v_add_co_u32_e32 v16, vcc, 0x1000, v80
	s_nop 1
	v_addc_co_u32_e32 v17, vcc, 0, v81, vcc
	global_store_dword v[16:17], v1, off offset:64
.LBB0_597:
	s_or_b64 exec, exec, s[2:3]
	v_mul_f32_e32 v1, v18, v0
	s_waitcnt lgkmcnt(0)
	s_nop 1
	v_mov_b32_dpp v16, v1 quad_perm:[1,0,3,2] row_mask:0xf bank_mask:0xf
	s_and_saveexec_b64 s[2:3], s[0:1]
	s_cbranch_execz .LBB0_599
	s_waitcnt lgkmcnt(0)
	v_cvt_pk_bf16_f32 v1, v1, v16
	v_add_co_u32_e32 v16, vcc, 0x1000, v80
	s_nop 1
	v_addc_co_u32_e32 v17, vcc, 0, v81, vcc
	global_store_dword v[16:17], v1, off offset:128
.LBB0_599:
	s_or_b64 exec, exec, s[2:3]
	v_mul_f32_e32 v0, v2, v0
	s_nop 1
	v_mov_b32_dpp v1, v0 quad_perm:[1,0,3,2] row_mask:0xf bank_mask:0xf
	s_and_saveexec_b64 s[2:3], s[0:1]
	s_cbranch_execz .LBB0_601
	s_waitcnt lgkmcnt(0)
	v_cvt_pk_bf16_f32 v2, v0, v1
	v_add_co_u32_e32 v0, vcc, 0x1000, v80
	s_nop 1
	v_addc_co_u32_e32 v1, vcc, 0, v81, vcc
	global_store_dword v[0:1], v2, off offset:192
.LBB0_601:
	s_or_b64 exec, exec, s[2:3]
	v_rcp_f32_e32 v0, v79
	s_waitcnt lgkmcnt(0)
	v_mul_f32_e32 v1, v35, v0
	s_nop 1
	v_mov_b32_dpp v2, v1 quad_perm:[1,0,3,2] row_mask:0xf bank_mask:0xf
	s_and_saveexec_b64 s[2:3], s[0:1]
	s_cbranch_execz .LBB0_603
	v_add_co_u32_e32 v16, vcc, 0x1000, v80
	s_waitcnt lgkmcnt(0)
	v_cvt_pk_bf16_f32 v1, v1, v2
	s_nop 0
	v_addc_co_u32_e32 v17, vcc, 0, v81, vcc
	global_store_dword v[16:17], v1, off offset:2048
.LBB0_603:
	s_or_b64 exec, exec, s[2:3]
	v_mul_f32_e32 v1, v51, v0
	s_waitcnt lgkmcnt(0)
	s_nop 1
	v_mov_b32_dpp v2, v1 quad_perm:[1,0,3,2] row_mask:0xf bank_mask:0xf
	s_and_saveexec_b64 s[2:3], s[0:1]
	s_cbranch_execz .LBB0_605
	v_add_co_u32_e32 v16, vcc, 0x1000, v80
	s_waitcnt lgkmcnt(0)
	v_cvt_pk_bf16_f32 v1, v1, v2
	s_nop 0
	v_addc_co_u32_e32 v17, vcc, 0, v81, vcc
	global_store_dword v[16:17], v1, off offset:2112
.LBB0_605:
	s_or_b64 exec, exec, s[2:3]
	v_mul_f32_e32 v1, v19, v0
	s_waitcnt lgkmcnt(0)
	s_nop 1
	v_mov_b32_dpp v2, v1 quad_perm:[1,0,3,2] row_mask:0xf bank_mask:0xf
	s_and_saveexec_b64 s[2:3], s[0:1]
	s_cbranch_execz .LBB0_607
	v_add_co_u32_e32 v16, vcc, 0x1000, v80
	s_waitcnt lgkmcnt(0)
	v_cvt_pk_bf16_f32 v1, v1, v2
	s_nop 0
	v_addc_co_u32_e32 v17, vcc, 0, v81, vcc
	global_store_dword v[16:17], v1, off offset:2176
.LBB0_607:
	s_or_b64 exec, exec, s[2:3]
	v_mul_f32_e32 v0, v3, v0
	s_nop 1
	v_mov_b32_dpp v1, v0 quad_perm:[1,0,3,2] row_mask:0xf bank_mask:0xf
	s_and_saveexec_b64 s[2:3], s[0:1]
	s_cbranch_execz .LBB0_609
	s_waitcnt lgkmcnt(0)
	v_cvt_pk_bf16_f32 v2, v0, v1
	v_add_co_u32_e32 v0, vcc, 0x1000, v80
	s_nop 1
	v_addc_co_u32_e32 v1, vcc, 0, v81, vcc
	global_store_dword v[0:1], v2, off offset:2240
.LBB0_609:
	s_or_b64 exec, exec, s[2:3]
	v_rcp_f32_e32 v0, v72
	s_waitcnt lgkmcnt(0)
	v_mul_f32_e32 v1, v36, v0
	s_nop 1
	v_mov_b32_dpp v2, v1 quad_perm:[1,0,3,2] row_mask:0xf bank_mask:0xf
	s_and_saveexec_b64 s[2:3], s[0:1]
	s_cbranch_execz .LBB0_611
	s_waitcnt lgkmcnt(0)
	v_cvt_pk_bf16_f32 v1, v1, v2
	v_add_co_u32_e32 v2, vcc, 0x4000, v80
	s_nop 1
	v_addc_co_u32_e32 v3, vcc, 0, v81, vcc
	global_store_dword v[2:3], v1, off
.LBB0_611:
	s_or_b64 exec, exec, s[2:3]
	v_mul_f32_e32 v1, v52, v0
	s_waitcnt lgkmcnt(0)
	s_nop 1
	v_mov_b32_dpp v2, v1 quad_perm:[1,0,3,2] row_mask:0xf bank_mask:0xf
	s_and_saveexec_b64 s[2:3], s[0:1]
	s_cbranch_execz .LBB0_613
	s_waitcnt lgkmcnt(0)
	v_cvt_pk_bf16_f32 v1, v1, v2
	v_add_co_u32_e32 v2, vcc, 0x4000, v80
	s_nop 1
	v_addc_co_u32_e32 v3, vcc, 0, v81, vcc
	global_store_dword v[2:3], v1, off offset:64
.LBB0_613:
	s_or_b64 exec, exec, s[2:3]
	v_mul_f32_e32 v1, v20, v0
	s_waitcnt lgkmcnt(0)
	s_nop 1
	v_mov_b32_dpp v2, v1 quad_perm:[1,0,3,2] row_mask:0xf bank_mask:0xf
	s_and_saveexec_b64 s[2:3], s[0:1]
	s_cbranch_execz .LBB0_615
	s_waitcnt lgkmcnt(0)
	v_cvt_pk_bf16_f32 v1, v1, v2
	v_add_co_u32_e32 v2, vcc, 0x4000, v80
	s_nop 1
	v_addc_co_u32_e32 v3, vcc, 0, v81, vcc
	global_store_dword v[2:3], v1, off offset:128
.LBB0_615:
	s_or_b64 exec, exec, s[2:3]
	v_mul_f32_e32 v0, v4, v0
	s_nop 1
	v_mov_b32_dpp v1, v0 quad_perm:[1,0,3,2] row_mask:0xf bank_mask:0xf
	s_and_saveexec_b64 s[2:3], s[0:1]
	s_cbranch_execz .LBB0_617
	s_waitcnt lgkmcnt(0)
	v_cvt_pk_bf16_f32 v2, v0, v1
	v_add_co_u32_e32 v0, vcc, 0x4000, v80
	s_nop 1
	v_addc_co_u32_e32 v1, vcc, 0, v81, vcc
	global_store_dword v[0:1], v2, off offset:192
.LBB0_617:
	s_or_b64 exec, exec, s[2:3]
	v_rcp_f32_e32 v0, v73
	s_waitcnt lgkmcnt(0)
	v_mul_f32_e32 v1, v37, v0
	s_nop 1
	v_mov_b32_dpp v2, v1 quad_perm:[1,0,3,2] row_mask:0xf bank_mask:0xf
	s_and_saveexec_b64 s[2:3], s[0:1]
	s_cbranch_execz .LBB0_619
	s_waitcnt lgkmcnt(0)
	v_cvt_pk_bf16_f32 v1, v1, v2
	v_add_co_u32_e32 v2, vcc, 0x4000, v80
	s_nop 1
	v_addc_co_u32_e32 v3, vcc, 0, v81, vcc
	global_store_dword v[2:3], v1, off offset:2048
.LBB0_619:
	s_or_b64 exec, exec, s[2:3]
	v_mul_f32_e32 v1, v53, v0
	s_waitcnt lgkmcnt(0)
	s_nop 1
	v_mov_b32_dpp v2, v1 quad_perm:[1,0,3,2] row_mask:0xf bank_mask:0xf
	s_and_saveexec_b64 s[2:3], s[0:1]
	s_cbranch_execz .LBB0_621
	s_waitcnt lgkmcnt(0)
	v_cvt_pk_bf16_f32 v1, v1, v2
	v_add_co_u32_e32 v2, vcc, 0x4000, v80
	s_nop 1
	v_addc_co_u32_e32 v3, vcc, 0, v81, vcc
	global_store_dword v[2:3], v1, off offset:2112
.LBB0_621:
	s_or_b64 exec, exec, s[2:3]
	v_mul_f32_e32 v1, v21, v0
	s_waitcnt lgkmcnt(0)
	s_nop 1
	v_mov_b32_dpp v2, v1 quad_perm:[1,0,3,2] row_mask:0xf bank_mask:0xf
	s_and_saveexec_b64 s[2:3], s[0:1]
	s_cbranch_execz .LBB0_623
	s_waitcnt lgkmcnt(0)
	v_cvt_pk_bf16_f32 v1, v1, v2
	v_add_co_u32_e32 v2, vcc, 0x4000, v80
	s_nop 1
	v_addc_co_u32_e32 v3, vcc, 0, v81, vcc
	global_store_dword v[2:3], v1, off offset:2176
; __device__ __forceinline__ int crow(int r, int hi) { return (r & 3) + 8 * (r >> 2) + 4 * hi; }
; __device__ __forceinline__ unsigned cvtpk(float lo, float hi) { unsigned r; asm volatile("v_cvt_pk_bf16_f32 %0, %1, %2" : "=v"(r) : "v"(lo), "v"(hi)); return r; }
; __device__ __forceinline__ int crow(int r, int hi) { return (r & 3) + 8 * (r >> 2) + 4 * hi; }
; __device__ __forceinline__ void attn_block(const BlockRef& cur, char* lds) {
;     ...
;     for (int r = 0; r < 16; ++r) { const int orow = crow(r, hi);
; #pragma unroll
;         for (int d0 = 0; d0 < 4; ++d0) { const float v = o[d0][r] * rli[r];
;             const float vn = __shfl_xor(v, 1);
;             if ((r32 & 1) == 0) *(unsigned*)(Ow + (size_t)orow * LDO + d0 * 32 + r32) = cvtpk(v, vn); } }
.LBB0_623:
	s_or_b64 exec, exec, s[2:3]
	v_mul_f32_e32 v0, v5, v0
	s_nop 1
	v_mov_b32_dpp v1, v0 quad_perm:[1,0,3,2] row_mask:0xf bank_mask:0xf
	s_and_saveexec_b64 s[2:3], s[0:1]
	s_cbranch_execz .LBB0_625
	s_waitcnt lgkmcnt(0)
	v_cvt_pk_bf16_f32 v2, v0, v1
	v_add_co_u32_e32 v0, vcc, 0x4000, v80
	s_nop 1
	v_addc_co_u32_e32 v1, vcc, 0, v81, vcc
	global_store_dword v[0:1], v2, off offset:2240
.LBB0_625:
	s_or_b64 exec, exec, s[2:3]
	v_rcp_f32_e32 v0, v74
	s_waitcnt lgkmcnt(0)
	v_mul_f32_e32 v1, v38, v0
	s_nop 1
	v_mov_b32_dpp v2, v1 quad_perm:[1,0,3,2] row_mask:0xf bank_mask:0xf
	s_and_saveexec_b64 s[2:3], s[0:1]
	s_cbranch_execz .LBB0_627
	s_waitcnt lgkmcnt(0)
	v_cvt_pk_bf16_f32 v1, v1, v2
	v_add_co_u32_e32 v2, vcc, 0x5000, v80
	s_nop 1
	v_addc_co_u32_e32 v3, vcc, 0, v81, vcc
	global_store_dword v[2:3], v1, off
.LBB0_627:
	s_or_b64 exec, exec, s[2:3]
	v_mul_f32_e32 v1, v54, v0
	s_waitcnt lgkmcnt(0)
	s_nop 1
	v_mov_b32_dpp v2, v1 quad_perm:[1,0,3,2] row_mask:0xf bank_mask:0xf
	s_and_saveexec_b64 s[2:3], s[0:1]
	s_cbranch_execz .LBB0_629
	s_waitcnt lgkmcnt(0)
	v_cvt_pk_bf16_f32 v1, v1, v2
	v_add_co_u32_e32 v2, vcc, 0x5000, v80
	s_nop 1
	v_addc_co_u32_e32 v3, vcc, 0, v81, vcc
	global_store_dword v[2:3], v1, off offset:64
.LBB0_629:
	s_or_b64 exec, exec, s[2:3]
	v_mul_f32_e32 v1, v22, v0
	s_waitcnt lgkmcnt(0)
	s_nop 1
	v_mov_b32_dpp v2, v1 quad_perm:[1,0,3,2] row_mask:0xf bank_mask:0xf
	s_and_saveexec_b64 s[2:3], s[0:1]
	s_cbranch_execz .LBB0_631
	s_waitcnt lgkmcnt(0)
	v_cvt_pk_bf16_f32 v1, v1, v2
	v_add_co_u32_e32 v2, vcc, 0x5000, v80
	s_nop 1
	v_addc_co_u32_e32 v3, vcc, 0, v81, vcc
	global_store_dword v[2:3], v1, off offset:128
.LBB0_631:
	s_or_b64 exec, exec, s[2:3]
	v_mul_f32_e32 v0, v6, v0
	s_nop 1
	v_mov_b32_dpp v1, v0 quad_perm:[1,0,3,2] row_mask:0xf bank_mask:0xf
	s_and_saveexec_b64 s[2:3], s[0:1]
	s_cbranch_execz .LBB0_633
	s_waitcnt lgkmcnt(0)
	v_cvt_pk_bf16_f32 v2, v0, v1
	v_add_co_u32_e32 v0, vcc, 0x5000, v80
	s_nop 1
	v_addc_co_u32_e32 v1, vcc, 0, v81, vcc
	global_store_dword v[0:1], v2, off offset:192
.LBB0_633:
	s_or_b64 exec, exec, s[2:3]
	v_rcp_f32_e32 v0, v75
	s_waitcnt lgkmcnt(0)
	v_mul_f32_e32 v1, v39, v0
	s_nop 1
	v_mov_b32_dpp v2, v1 quad_perm:[1,0,3,2] row_mask:0xf bank_mask:0xf
	s_and_saveexec_b64 s[2:3], s[0:1]
	s_cbranch_execz .LBB0_635
	s_waitcnt lgkmcnt(0)
	v_cvt_pk_bf16_f32 v1, v1, v2
	v_add_co_u32_e32 v2, vcc, 0x5000, v80
	s_nop 1
	v_addc_co_u32_e32 v3, vcc, 0, v81, vcc
	global_store_dword v[2:3], v1, off offset:2048
.LBB0_635:
	s_or_b64 exec, exec, s[2:3]
	v_mul_f32_e32 v1, v55, v0
	s_waitcnt lgkmcnt(0)
	s_nop 1
	v_mov_b32_dpp v2, v1 quad_perm:[1,0,3,2] row_mask:0xf bank_mask:0xf
	s_and_saveexec_b64 s[2:3], s[0:1]
	s_cbranch_execz .LBB0_637
	s_waitcnt lgkmcnt(0)
	v_cvt_pk_bf16_f32 v1, v1, v2
	v_add_co_u32_e32 v2, vcc, 0x5000, v80
	s_nop 1
	v_addc_co_u32_e32 v3, vcc, 0, v81, vcc
	global_store_dword v[2:3], v1, off offset:2112
.LBB0_637:
	s_or_b64 exec, exec, s[2:3]
	v_mul_f32_e32 v1, v23, v0
	s_waitcnt lgkmcnt(0)
	s_nop 1
	v_mov_b32_dpp v2, v1 quad_perm:[1,0,3,2] row_mask:0xf bank_mask:0xf
	s_and_saveexec_b64 s[2:3], s[0:1]
	s_cbranch_execz .LBB0_639
	s_waitcnt lgkmcnt(0)
	v_cvt_pk_bf16_f32 v1, v1, v2
	v_add_co_u32_e32 v2, vcc, 0x5000, v80
	s_nop 1
	v_addc_co_u32_e32 v3, vcc, 0, v81, vcc
	global_store_dword v[2:3], v1, off offset:2176
.LBB0_639:
	s_or_b64 exec, exec, s[2:3]
	v_mul_f32_e32 v0, v7, v0
	s_nop 1
	v_mov_b32_dpp v1, v0 quad_perm:[1,0,3,2] row_mask:0xf bank_mask:0xf
	s_and_saveexec_b64 s[2:3], s[0:1]
	s_cbranch_execz .LBB0_641
	s_waitcnt lgkmcnt(0)
	v_cvt_pk_bf16_f32 v2, v0, v1
	v_add_co_u32_e32 v0, vcc, 0x5000, v80
	s_nop 1
	v_addc_co_u32_e32 v1, vcc, 0, v81, vcc
	global_store_dword v[0:1], v2, off offset:2240
.LBB0_641:
	s_or_b64 exec, exec, s[2:3]
	v_rcp_f32_e32 v0, v68
	s_waitcnt lgkmcnt(0)
	v_mul_f32_e32 v1, v40, v0
	s_nop 1
	v_mov_b32_dpp v2, v1 quad_perm:[1,0,3,2] row_mask:0xf bank_mask:0xf
	s_and_saveexec_b64 s[2:3], s[0:1]
	s_cbranch_execz .LBB0_643
	s_waitcnt lgkmcnt(0)
	v_cvt_pk_bf16_f32 v1, v1, v2
	v_add_co_u32_e32 v2, vcc, 0x8000, v80
	s_nop 1
	v_addc_co_u32_e32 v3, vcc, 0, v81, vcc
	global_store_dword v[2:3], v1, off
.LBB0_643:
	s_or_b64 exec, exec, s[2:3]
	v_mul_f32_e32 v1, v56, v0
	s_waitcnt lgkmcnt(0)
	s_nop 1
	v_mov_b32_dpp v2, v1 quad_perm:[1,0,3,2] row_mask:0xf bank_mask:0xf
	s_and_saveexec_b64 s[2:3], s[0:1]
	s_cbranch_execz .LBB0_645
	s_waitcnt lgkmcnt(0)
	v_cvt_pk_bf16_f32 v1, v1, v2
	v_add_co_u32_e32 v2, vcc, 0x8000, v80
	s_nop 1
	v_addc_co_u32_e32 v3, vcc, 0, v81, vcc
	global_store_dword v[2:3], v1, off offset:64
.LBB0_645:
	s_or_b64 exec, exec, s[2:3]
	v_mul_f32_e32 v1, v24, v0
	s_waitcnt lgkmcnt(0)
	s_nop 1
	v_mov_b32_dpp v2, v1 quad_perm:[1,0,3,2] row_mask:0xf bank_mask:0xf
	s_and_saveexec_b64 s[2:3], s[0:1]
	s_cbranch_execz .LBB0_647
	s_waitcnt lgkmcnt(0)
	v_cvt_pk_bf16_f32 v1, v1, v2
	v_add_co_u32_e32 v2, vcc, 0x8000, v80
	s_nop 1
	v_addc_co_u32_e32 v3, vcc, 0, v81, vcc
	global_store_dword v[2:3], v1, off offset:128
.LBB0_647:
	s_or_b64 exec, exec, s[2:3]
	v_mul_f32_e32 v0, v8, v0
	s_nop 1
	v_mov_b32_dpp v1, v0 quad_perm:[1,0,3,2] row_mask:0xf bank_mask:0xf
	s_and_saveexec_b64 s[2:3], s[0:1]
	s_cbranch_execz .LBB0_649
	s_waitcnt lgkmcnt(0)
	v_cvt_pk_bf16_f32 v2, v0, v1
	v_add_co_u32_e32 v0, vcc, 0x8000, v80
	s_nop 1
	v_addc_co_u32_e32 v1, vcc, 0, v81, vcc
	global_store_dword v[0:1], v2, off offset:192
.LBB0_649:
	s_or_b64 exec, exec, s[2:3]
	v_rcp_f32_e32 v0, v69
	s_waitcnt lgkmcnt(0)
	v_mul_f32_e32 v1, v41, v0
	s_nop 1
	v_mov_b32_dpp v2, v1 quad_perm:[1,0,3,2] row_mask:0xf bank_mask:0xf
	s_and_saveexec_b64 s[2:3], s[0:1]
	s_cbranch_execz .LBB0_651
	s_waitcnt lgkmcnt(0)
	v_cvt_pk_bf16_f32 v1, v1, v2
	v_add_co_u32_e32 v2, vcc, 0x8000, v80
	s_nop 1
	v_addc_co_u32_e32 v3, vcc, 0, v81, vcc
	global_store_dword v[2:3], v1, off offset:2048
; __device__ __forceinline__ int crow(int r, int hi) { return (r & 3) + 8 * (r >> 2) + 4 * hi; }
; __device__ __forceinline__ unsigned cvtpk(float lo, float hi) { unsigned r; asm volatile("v_cvt_pk_bf16_f32 %0, %1, %2" : "=v"(r) : "v"(lo), "v"(hi)); return r; }
; __device__ __forceinline__ int crow(int r, int hi) { return (r & 3) + 8 * (r >> 2) + 4 * hi; }
; __device__ __forceinline__ void attn_block(const BlockRef& cur, char* lds) {
;     ...
;     for (int r = 0; r < 16; ++r) { const int orow = crow(r, hi);
; #pragma unroll
;         for (int d0 = 0; d0 < 4; ++d0) { const float v = o[d0][r] * rli[r];
;             const float vn = __shfl_xor(v, 1);
;             if ((r32 & 1) == 0) *(unsigned*)(Ow + (size_t)orow * LDO + d0 * 32 + r32) = cvtpk(v, vn); } }
.LBB0_651:
	s_or_b64 exec, exec, s[2:3]
	v_mul_f32_e32 v1, v57, v0
	s_waitcnt lgkmcnt(0)
	s_nop 1
	v_mov_b32_dpp v2, v1 quad_perm:[1,0,3,2] row_mask:0xf bank_mask:0xf
	s_and_saveexec_b64 s[2:3], s[0:1]
	s_cbranch_execz .LBB0_653
	s_waitcnt lgkmcnt(0)
	v_cvt_pk_bf16_f32 v1, v1, v2
	v_add_co_u32_e32 v2, vcc, 0x8000, v80
	s_nop 1
	v_addc_co_u32_e32 v3, vcc, 0, v81, vcc
	global_store_dword v[2:3], v1, off offset:2112
.LBB0_653:
	s_or_b64 exec, exec, s[2:3]
	v_mul_f32_e32 v1, v25, v0
	s_waitcnt lgkmcnt(0)
	s_nop 1
	v_mov_b32_dpp v2, v1 quad_perm:[1,0,3,2] row_mask:0xf bank_mask:0xf
	s_and_saveexec_b64 s[2:3], s[0:1]
	s_cbranch_execz .LBB0_655
	s_waitcnt lgkmcnt(0)
	v_cvt_pk_bf16_f32 v1, v1, v2
	v_add_co_u32_e32 v2, vcc, 0x8000, v80
	s_nop 1
	v_addc_co_u32_e32 v3, vcc, 0, v81, vcc
	global_store_dword v[2:3], v1, off offset:2176
.LBB0_655:
	s_or_b64 exec, exec, s[2:3]
	v_mul_f32_e32 v0, v9, v0
	s_nop 1
	v_mov_b32_dpp v1, v0 quad_perm:[1,0,3,2] row_mask:0xf bank_mask:0xf
	s_and_saveexec_b64 s[2:3], s[0:1]
	s_cbranch_execz .LBB0_657
	s_waitcnt lgkmcnt(0)
	v_cvt_pk_bf16_f32 v2, v0, v1
	v_add_co_u32_e32 v0, vcc, 0x8000, v80
	s_nop 1
	v_addc_co_u32_e32 v1, vcc, 0, v81, vcc
	global_store_dword v[0:1], v2, off offset:2240
.LBB0_657:
	s_or_b64 exec, exec, s[2:3]
	v_rcp_f32_e32 v0, v70
	s_waitcnt lgkmcnt(0)
	v_mul_f32_e32 v1, v42, v0
	s_nop 1
	v_mov_b32_dpp v2, v1 quad_perm:[1,0,3,2] row_mask:0xf bank_mask:0xf
	s_and_saveexec_b64 s[2:3], s[0:1]
	s_cbranch_execz .LBB0_659
	s_waitcnt lgkmcnt(0)
	v_cvt_pk_bf16_f32 v1, v1, v2
	v_add_co_u32_e32 v2, vcc, 0x9000, v80
	s_nop 1
	v_addc_co_u32_e32 v3, vcc, 0, v81, vcc
	global_store_dword v[2:3], v1, off
.LBB0_659:
	s_or_b64 exec, exec, s[2:3]
	v_mul_f32_e32 v1, v58, v0
	s_waitcnt lgkmcnt(0)
	s_nop 1
	v_mov_b32_dpp v2, v1 quad_perm:[1,0,3,2] row_mask:0xf bank_mask:0xf
	s_and_saveexec_b64 s[2:3], s[0:1]
	s_cbranch_execz .LBB0_661
	s_waitcnt lgkmcnt(0)
	v_cvt_pk_bf16_f32 v1, v1, v2
	v_add_co_u32_e32 v2, vcc, 0x9000, v80
	s_nop 1
	v_addc_co_u32_e32 v3, vcc, 0, v81, vcc
	global_store_dword v[2:3], v1, off offset:64
.LBB0_661:
	s_or_b64 exec, exec, s[2:3]
	v_mul_f32_e32 v1, v26, v0
	s_waitcnt lgkmcnt(0)
	s_nop 1
	v_mov_b32_dpp v2, v1 quad_perm:[1,0,3,2] row_mask:0xf bank_mask:0xf
	s_and_saveexec_b64 s[2:3], s[0:1]
	s_cbranch_execz .LBB0_663
	s_waitcnt lgkmcnt(0)
	v_cvt_pk_bf16_f32 v1, v1, v2
	v_add_co_u32_e32 v2, vcc, 0x9000, v80
	s_nop 1
	v_addc_co_u32_e32 v3, vcc, 0, v81, vcc
	global_store_dword v[2:3], v1, off offset:128
.LBB0_663:
	s_or_b64 exec, exec, s[2:3]
	v_mul_f32_e32 v0, v10, v0
	s_nop 1
	v_mov_b32_dpp v1, v0 quad_perm:[1,0,3,2] row_mask:0xf bank_mask:0xf
	s_and_saveexec_b64 s[2:3], s[0:1]
	s_cbranch_execz .LBB0_665
	s_waitcnt lgkmcnt(0)
	v_cvt_pk_bf16_f32 v2, v0, v1
	v_add_co_u32_e32 v0, vcc, 0x9000, v80
	s_nop 1
	v_addc_co_u32_e32 v1, vcc, 0, v81, vcc
	global_store_dword v[0:1], v2, off offset:192
.LBB0_665:
	s_or_b64 exec, exec, s[2:3]
	v_rcp_f32_e32 v0, v71
	s_waitcnt lgkmcnt(0)
	v_mul_f32_e32 v1, v43, v0
	s_nop 1
	v_mov_b32_dpp v2, v1 quad_perm:[1,0,3,2] row_mask:0xf bank_mask:0xf
	s_and_saveexec_b64 s[2:3], s[0:1]
	s_cbranch_execz .LBB0_667
	s_waitcnt lgkmcnt(0)
	v_cvt_pk_bf16_f32 v1, v1, v2
	v_add_co_u32_e32 v2, vcc, 0x9000, v80
	s_nop 1
	v_addc_co_u32_e32 v3, vcc, 0, v81, vcc
	global_store_dword v[2:3], v1, off offset:2048
.LBB0_667:
	s_or_b64 exec, exec, s[2:3]
	v_mul_f32_e32 v1, v59, v0
	s_waitcnt lgkmcnt(0)
	s_nop 1
	v_mov_b32_dpp v2, v1 quad_perm:[1,0,3,2] row_mask:0xf bank_mask:0xf
	s_and_saveexec_b64 s[2:3], s[0:1]
	s_cbranch_execz .LBB0_669
	s_waitcnt lgkmcnt(0)
	v_cvt_pk_bf16_f32 v1, v1, v2
	v_add_co_u32_e32 v2, vcc, 0x9000, v80
	s_nop 1
	v_addc_co_u32_e32 v3, vcc, 0, v81, vcc
	global_store_dword v[2:3], v1, off offset:2112
.LBB0_669:
	s_or_b64 exec, exec, s[2:3]
	v_mul_f32_e32 v1, v27, v0
	s_waitcnt lgkmcnt(0)
	s_nop 1
	v_mov_b32_dpp v2, v1 quad_perm:[1,0,3,2] row_mask:0xf bank_mask:0xf
	s_and_saveexec_b64 s[2:3], s[0:1]
	s_cbranch_execz .LBB0_671
	s_waitcnt lgkmcnt(0)
	v_cvt_pk_bf16_f32 v1, v1, v2
	v_add_co_u32_e32 v2, vcc, 0x9000, v80
	s_nop 1
	v_addc_co_u32_e32 v3, vcc, 0, v81, vcc
	global_store_dword v[2:3], v1, off offset:2176
.LBB0_671:
	s_or_b64 exec, exec, s[2:3]
	v_mul_f32_e32 v0, v11, v0
	s_nop 1
	v_mov_b32_dpp v1, v0 quad_perm:[1,0,3,2] row_mask:0xf bank_mask:0xf
	s_and_saveexec_b64 s[2:3], s[0:1]
	s_cbranch_execz .LBB0_673
	s_waitcnt lgkmcnt(0)
	v_cvt_pk_bf16_f32 v2, v0, v1
	v_add_co_u32_e32 v0, vcc, 0x9000, v80
	s_nop 1
	v_addc_co_u32_e32 v1, vcc, 0, v81, vcc
	global_store_dword v[0:1], v2, off offset:2240
.LBB0_673:
	s_or_b64 exec, exec, s[2:3]
	v_rcp_f32_e32 v0, v64
	s_waitcnt lgkmcnt(0)
	v_mul_f32_e32 v1, v44, v0
	s_nop 1
	v_mov_b32_dpp v2, v1 quad_perm:[1,0,3,2] row_mask:0xf bank_mask:0xf
	s_and_saveexec_b64 s[2:3], s[0:1]
	s_cbranch_execz .LBB0_675
	s_waitcnt lgkmcnt(0)
	v_cvt_pk_bf16_f32 v1, v1, v2
	v_add_co_u32_e32 v2, vcc, 0xc000, v80
	s_nop 1
	v_addc_co_u32_e32 v3, vcc, 0, v81, vcc
	global_store_dword v[2:3], v1, off
.LBB0_675:
	s_or_b64 exec, exec, s[2:3]
	v_mul_f32_e32 v1, v60, v0
	s_waitcnt lgkmcnt(0)
	s_nop 1
	v_mov_b32_dpp v2, v1 quad_perm:[1,0,3,2] row_mask:0xf bank_mask:0xf
	s_and_saveexec_b64 s[2:3], s[0:1]
	s_cbranch_execz .LBB0_677
	s_waitcnt lgkmcnt(0)
	v_cvt_pk_bf16_f32 v1, v1, v2
	v_add_co_u32_e32 v2, vcc, 0xc000, v80
	s_nop 1
	v_addc_co_u32_e32 v3, vcc, 0, v81, vcc
	global_store_dword v[2:3], v1, off offset:64
; __device__ __forceinline__ int crow(int r, int hi) { return (r & 3) + 8 * (r >> 2) + 4 * hi; }
; __device__ __forceinline__ unsigned cvtpk(float lo, float hi) { unsigned r; asm volatile("v_cvt_pk_bf16_f32 %0, %1, %2" : "=v"(r) : "v"(lo), "v"(hi)); return r; }
; __device__ __forceinline__ int crow(int r, int hi) { return (r & 3) + 8 * (r >> 2) + 4 * hi; }
; __device__ __forceinline__ void attn_block(const BlockRef& cur, char* lds) {
;     ...
;     for (int r = 0; r < 16; ++r) { const int orow = crow(r, hi);
; #pragma unroll
;         for (int d0 = 0; d0 < 4; ++d0) { const float v = o[d0][r] * rli[r];
;             const float vn = __shfl_xor(v, 1);
;             if ((r32 & 1) == 0) *(unsigned*)(Ow + (size_t)orow * LDO + d0 * 32 + r32) = cvtpk(v, vn); } }
.LBB0_677:
	s_or_b64 exec, exec, s[2:3]
	v_mul_f32_e32 v1, v28, v0
	s_waitcnt lgkmcnt(0)
	s_nop 1
	v_mov_b32_dpp v2, v1 quad_perm:[1,0,3,2] row_mask:0xf bank_mask:0xf
	s_and_saveexec_b64 s[2:3], s[0:1]
	s_cbranch_execz .LBB0_679
	s_waitcnt lgkmcnt(0)
	v_cvt_pk_bf16_f32 v1, v1, v2
	v_add_co_u32_e32 v2, vcc, 0xc000, v80
	s_nop 1
	v_addc_co_u32_e32 v3, vcc, 0, v81, vcc
	global_store_dword v[2:3], v1, off offset:128
.LBB0_679:
	s_or_b64 exec, exec, s[2:3]
	v_mul_f32_e32 v0, v12, v0
	s_nop 1
	v_mov_b32_dpp v1, v0 quad_perm:[1,0,3,2] row_mask:0xf bank_mask:0xf
	s_and_saveexec_b64 s[2:3], s[0:1]
	s_cbranch_execz .LBB0_681
	s_waitcnt lgkmcnt(0)
	v_cvt_pk_bf16_f32 v2, v0, v1
	v_add_co_u32_e32 v0, vcc, 0xc000, v80
	s_nop 1
	v_addc_co_u32_e32 v1, vcc, 0, v81, vcc
	global_store_dword v[0:1], v2, off offset:192
.LBB0_681:
	s_or_b64 exec, exec, s[2:3]
	v_rcp_f32_e32 v0, v65
	s_waitcnt lgkmcnt(0)
	v_mul_f32_e32 v1, v45, v0
	s_nop 1
	v_mov_b32_dpp v2, v1 quad_perm:[1,0,3,2] row_mask:0xf bank_mask:0xf
	s_and_saveexec_b64 s[2:3], s[0:1]
	s_cbranch_execz .LBB0_683
	s_waitcnt lgkmcnt(0)
	v_cvt_pk_bf16_f32 v1, v1, v2
	v_add_co_u32_e32 v2, vcc, 0xc000, v80
	s_nop 1
	v_addc_co_u32_e32 v3, vcc, 0, v81, vcc
	global_store_dword v[2:3], v1, off offset:2048
.LBB0_683:
	s_or_b64 exec, exec, s[2:3]
	v_mul_f32_e32 v1, v61, v0
	s_waitcnt lgkmcnt(0)
	s_nop 1
	v_mov_b32_dpp v2, v1 quad_perm:[1,0,3,2] row_mask:0xf bank_mask:0xf
	s_and_saveexec_b64 s[2:3], s[0:1]
	s_cbranch_execz .LBB0_685
	s_waitcnt lgkmcnt(0)
	v_cvt_pk_bf16_f32 v1, v1, v2
	v_add_co_u32_e32 v2, vcc, 0xc000, v80
	s_nop 1
	v_addc_co_u32_e32 v3, vcc, 0, v81, vcc
	global_store_dword v[2:3], v1, off offset:2112
.LBB0_685:
	s_or_b64 exec, exec, s[2:3]
	v_mul_f32_e32 v1, v29, v0
	s_waitcnt lgkmcnt(0)
	s_nop 1
	v_mov_b32_dpp v2, v1 quad_perm:[1,0,3,2] row_mask:0xf bank_mask:0xf
	s_and_saveexec_b64 s[2:3], s[0:1]
	s_cbranch_execz .LBB0_687
	s_waitcnt lgkmcnt(0)
	v_cvt_pk_bf16_f32 v1, v1, v2
	v_add_co_u32_e32 v2, vcc, 0xc000, v80
	s_nop 1
	v_addc_co_u32_e32 v3, vcc, 0, v81, vcc
	global_store_dword v[2:3], v1, off offset:2176
.LBB0_687:
	s_or_b64 exec, exec, s[2:3]
	v_mul_f32_e32 v0, v13, v0
	s_nop 1
	v_mov_b32_dpp v1, v0 quad_perm:[1,0,3,2] row_mask:0xf bank_mask:0xf
	s_and_saveexec_b64 s[2:3], s[0:1]
	s_cbranch_execz .LBB0_689
	s_waitcnt lgkmcnt(0)
	v_cvt_pk_bf16_f32 v2, v0, v1
	v_add_co_u32_e32 v0, vcc, 0xc000, v80
	s_nop 1
	v_addc_co_u32_e32 v1, vcc, 0, v81, vcc
	global_store_dword v[0:1], v2, off offset:2240
.LBB0_689:
	s_or_b64 exec, exec, s[2:3]
	v_rcp_f32_e32 v0, v66
	s_waitcnt lgkmcnt(0)
	v_mul_f32_e32 v1, v46, v0
	s_nop 1
	v_mov_b32_dpp v2, v1 quad_perm:[1,0,3,2] row_mask:0xf bank_mask:0xf
	s_and_saveexec_b64 s[2:3], s[0:1]
	s_cbranch_execz .LBB0_691
	s_waitcnt lgkmcnt(0)
	v_cvt_pk_bf16_f32 v1, v1, v2
	v_add_co_u32_e32 v2, vcc, 0xd000, v80
	s_nop 1
	v_addc_co_u32_e32 v3, vcc, 0, v81, vcc
	global_store_dword v[2:3], v1, off
.LBB0_691:
	s_or_b64 exec, exec, s[2:3]
	v_mul_f32_e32 v1, v62, v0
	s_waitcnt lgkmcnt(0)
	s_nop 1
	v_mov_b32_dpp v2, v1 quad_perm:[1,0,3,2] row_mask:0xf bank_mask:0xf
	s_and_saveexec_b64 s[2:3], s[0:1]
	s_cbranch_execz .LBB0_693
	s_waitcnt lgkmcnt(0)
	v_cvt_pk_bf16_f32 v1, v1, v2
	v_add_co_u32_e32 v2, vcc, 0xd000, v80
	s_nop 1
	v_addc_co_u32_e32 v3, vcc, 0, v81, vcc
	global_store_dword v[2:3], v1, off offset:64
.LBB0_693:
	s_or_b64 exec, exec, s[2:3]
	v_mul_f32_e32 v1, v30, v0
	s_waitcnt lgkmcnt(0)
	s_nop 1
	v_mov_b32_dpp v2, v1 quad_perm:[1,0,3,2] row_mask:0xf bank_mask:0xf
	s_and_saveexec_b64 s[2:3], s[0:1]
	s_cbranch_execz .LBB0_695
	s_waitcnt lgkmcnt(0)
	v_cvt_pk_bf16_f32 v1, v1, v2
	v_add_co_u32_e32 v2, vcc, 0xd000, v80
	s_nop 1
	v_addc_co_u32_e32 v3, vcc, 0, v81, vcc
	global_store_dword v[2:3], v1, off offset:128
.LBB0_695:
	s_or_b64 exec, exec, s[2:3]
	v_mul_f32_e32 v0, v14, v0
	s_nop 1
	v_mov_b32_dpp v1, v0 quad_perm:[1,0,3,2] row_mask:0xf bank_mask:0xf
	s_and_saveexec_b64 s[2:3], s[0:1]
	s_cbranch_execz .LBB0_697
	s_waitcnt lgkmcnt(0)
	v_cvt_pk_bf16_f32 v2, v0, v1
	v_add_co_u32_e32 v0, vcc, 0xd000, v80
	s_nop 1
	v_addc_co_u32_e32 v1, vcc, 0, v81, vcc
	global_store_dword v[0:1], v2, off offset:192
.LBB0_697:
	s_or_b64 exec, exec, s[2:3]
	v_rcp_f32_e32 v0, v67
	s_waitcnt lgkmcnt(0)
	v_mul_f32_e32 v1, v47, v0
	s_nop 1
	v_mov_b32_dpp v2, v1 quad_perm:[1,0,3,2] row_mask:0xf bank_mask:0xf
	s_and_saveexec_b64 s[2:3], s[0:1]
	s_cbranch_execz .LBB0_699
	s_waitcnt lgkmcnt(0)
	v_cvt_pk_bf16_f32 v1, v1, v2
	v_add_co_u32_e32 v2, vcc, 0xd000, v80
	s_nop 1
	v_addc_co_u32_e32 v3, vcc, 0, v81, vcc
	global_store_dword v[2:3], v1, off offset:2048
.LBB0_699:
	s_or_b64 exec, exec, s[2:3]
	v_mul_f32_e32 v1, v63, v0
	s_waitcnt lgkmcnt(0)
	s_nop 1
	v_mov_b32_dpp v2, v1 quad_perm:[1,0,3,2] row_mask:0xf bank_mask:0xf
	s_and_saveexec_b64 s[2:3], s[0:1]
	s_cbranch_execz .LBB0_701
	s_waitcnt lgkmcnt(0)
	v_cvt_pk_bf16_f32 v1, v1, v2
	v_add_co_u32_e32 v2, vcc, 0xd000, v80
	s_nop 1
	v_addc_co_u32_e32 v3, vcc, 0, v81, vcc
	global_store_dword v[2:3], v1, off offset:2112
.LBB0_701:
	s_or_b64 exec, exec, s[2:3]
	v_mul_f32_e32 v1, v31, v0
	s_waitcnt lgkmcnt(0)
	s_nop 1
	v_mov_b32_dpp v2, v1 quad_perm:[1,0,3,2] row_mask:0xf bank_mask:0xf
	s_and_saveexec_b64 s[2:3], s[0:1]
	s_cbranch_execz .LBB0_703
	s_waitcnt lgkmcnt(0)
	v_cvt_pk_bf16_f32 v1, v1, v2
	v_add_co_u32_e32 v2, vcc, 0xd000, v80
	s_nop 1
	v_addc_co_u32_e32 v3, vcc, 0, v81, vcc
	global_store_dword v[2:3], v1, off offset:2176
.LBB0_703:
	s_or_b64 exec, exec, s[2:3]
	v_mul_f32_e32 v0, v15, v0
	s_nop 1
	v_mov_b32_dpp v1, v0 quad_perm:[1,0,3,2] row_mask:0xf bank_mask:0xf
	s_and_saveexec_b64 s[2:3], s[0:1]
	s_cbranch_execz .LBB0_705
	s_waitcnt lgkmcnt(0)
	v_cvt_pk_bf16_f32 v2, v0, v1
	v_add_co_u32_e32 v0, vcc, 0xd000, v80
	s_nop 1
	v_addc_co_u32_e32 v1, vcc, 0, v81, vcc
	global_store_dword v[0:1], v2, off offset:2240

; #define SBAR() __builtin_amdgcn_sched_barrier(0)
; #define RD8(S, d0) do { constexpr int b_ = v_rd_off(d0, 0, 0); TRRD(S##l0, b_); TRRD(S##h0, b_ + 2048); TRRD(S##l1, b_ + 4096); TRRD(S##h1, b_ + 6144); \
;         TRRD(S##l2, b_ + 8192); TRRD(S##h2, b_ + 10240); TRRD(S##l3, b_ + 12288); TRRD(S##h3, b_ + 14336); } while (0)
; #define RD8(S, d0) do { constexpr int b_ = v_rd_off(d0, 0, 0); TRRD(S##l0, b_); TRRD(S##h0, b_ + 2048); TRRD(S##l1, b_ + 4096); TRRD(S##h1, b_ + 6144); \
;         TRRD(S##l2, b_ + 8192); TRRD(S##h2, b_ + 10240); TRRD(S##l3, b_ + 12288); TRRD(S##h3, b_ + 14336); } while (0)
; __device__ __forceinline__ void finishSM(f32x16& p0, f32x16& p1, float alpha, float& l_reg, bf16x8& pa0, bf16x8& pa1, bf16x8& pa2, bf16x8& pa3) {
;     for (int r = 0; r < 16; ++r) p1[r] = __builtin_amdgcn_exp2f(p1[r]);
;     float ps = 0; for (int r = 0; r < 16; ++r) ps += p0[r]; for (int r = 0; r < 16; ++r) ps += p1[r];
;     { auto rr = __builtin_amdgcn_permlane32_swap(__float_as_uint(ps), __float_as_uint(ps), false, false);
;       ps = __uint_as_float(rr[0]) + __uint_as_float(rr[1]); }
;     l_reg = l_reg * alpha + ps;
;     ...
;     PK4(p0, 0, pa0); PK4(p0, 8, pa1); PK4(p1, 0, pa2); PK4(p1, 8, pa3);
; __device__ __forceinline__ void pv_part(f32x16* o, int vb, bf16x8 pa0, bf16x8 pa1, bf16x8 pa2, bf16x8 pa3, f32x16& x0, f32x16& x1, float& m_reg, float& mn, float& alpha) {
;     ...
;     const float mnL = -mn * C2;
;     SBAR();
;     RD8(B, 3);
;     asm volatile("s_waitcnt lgkmcnt(8)" ::: "memory"); SBAR(); MM4(A, 2);
; #pragma unroll
;     for (int r = 0; r < 16; ++r) x0[r] = fmaf(x0[r], C2, mnL);
; #pragma unroll
;     for (int r = 0; r < 16; ++r) x1[r] = fmaf(x1[r], C2, mnL);
; #pragma unroll
;     for (int r = 0; r < 6; ++r) x0[r] = __builtin_amdgcn_exp2f(x0[r]);
;     SBAR();
;     asm volatile("s_waitcnt lgkmcnt(0)" ::: "memory"); SBAR(); MM4(B, 3);
; #pragma unroll
;     for (int r = 6; r < 16; ++r) x0[r] = __builtin_amdgcn_exp2f(x0[r]);
.LBB0_743:
	v_cndmask_b32_e64 v96, v115, v189, s[4:5]
	v_mul_f32_e32 v96, 0xbdd53b94, v96
	v_fmamk_f32 v80, v80, 0x3dd53b94, v96
	v_fmamk_f32 v81, v81, 0x3dd53b94, v96
	v_fmamk_f32 v82, v82, 0x3dd53b94, v96
	v_fmamk_f32 v83, v83, 0x3dd53b94, v96
	v_fmamk_f32 v84, v84, 0x3dd53b94, v96
	v_fmamk_f32 v85, v85, 0x3dd53b94, v96
	v_fmamk_f32 v86, v86, 0x3dd53b94, v96
	v_fmamk_f32 v87, v87, 0x3dd53b94, v96
	v_fmamk_f32 v88, v88, 0x3dd53b94, v96
	v_fmamk_f32 v89, v89, 0x3dd53b94, v96
	v_fmamk_f32 v90, v90, 0x3dd53b94, v96
	v_fmamk_f32 v91, v91, 0x3dd53b94, v96
	v_fmamk_f32 v92, v92, 0x3dd53b94, v96
	v_fmamk_f32 v93, v93, 0x3dd53b94, v96
	v_fmamk_f32 v94, v94, 0x3dd53b94, v96
	v_fmamk_f32 v95, v95, 0x3dd53b94, v96
	v_fmamk_f32 v64, v64, 0x3dd53b94, v96
	v_fmamk_f32 v65, v65, 0x3dd53b94, v96
	v_fmamk_f32 v66, v66, 0x3dd53b94, v96
	v_fmamk_f32 v67, v67, 0x3dd53b94, v96
	v_fmamk_f32 v68, v68, 0x3dd53b94, v96
	v_fmamk_f32 v69, v69, 0x3dd53b94, v96
	v_fmamk_f32 v70, v70, 0x3dd53b94, v96
	v_fmamk_f32 v71, v71, 0x3dd53b94, v96
	v_fmamk_f32 v72, v72, 0x3dd53b94, v96
	v_fmamk_f32 v73, v73, 0x3dd53b94, v96
	v_fmamk_f32 v74, v74, 0x3dd53b94, v96
	v_fmamk_f32 v75, v75, 0x3dd53b94, v96
	v_fmamk_f32 v76, v76, 0x3dd53b94, v96
	v_fmamk_f32 v77, v77, 0x3dd53b94, v96
	v_fmamk_f32 v78, v78, 0x3dd53b94, v96
	v_fmac_f32_e32 v96, 0x3dd53b94, v79
	v_exp_f32_e32 v79, v80
	v_exp_f32_e32 v80, v81
	v_exp_f32_e32 v81, v82
	v_exp_f32_e32 v82, v83
	v_exp_f32_e32 v83, v84
	v_exp_f32_e32 v84, v85
	v_exp_f32_e32 v85, v86
	v_exp_f32_e32 v86, v87
	v_exp_f32_e32 v87, v88
	v_exp_f32_e32 v88, v89
	v_exp_f32_e32 v89, v90
	v_exp_f32_e32 v90, v91
	v_exp_f32_e32 v91, v92
	v_exp_f32_e32 v92, v93
	v_exp_f32_e32 v93, v94
	v_exp_f32_e32 v94, v95
	v_exp_f32_e32 v95, v64
	v_add_f32_e32 v64, 0, v79
	v_add_f32_e32 v64, v80, v64
	v_add_f32_e32 v64, v81, v64
	v_add_f32_e32 v64, v82, v64
	v_add_f32_e32 v64, v83, v64
	v_add_f32_e32 v64, v84, v64
	v_add_f32_e32 v64, v85, v64
	v_add_f32_e32 v64, v86, v64
	v_add_f32_e32 v64, v87, v64
	v_add_f32_e32 v64, v88, v64
	v_add_f32_e32 v64, v89, v64
	v_add_f32_e32 v64, v90, v64
	v_add_f32_e32 v64, v91, v64
	v_exp_f32_e32 v97, v65
	v_add_f32_e32 v64, v92, v64
	v_exp_f32_e32 v98, v66
	v_add_f32_e32 v64, v93, v64
	v_exp_f32_e32 v99, v67
	v_add_f32_e32 v64, v94, v64
	v_exp_f32_e32 v100, v68
	v_add_f32_e32 v64, v95, v64
	v_exp_f32_e32 v101, v69
	v_add_f32_e32 v64, v97, v64
	v_exp_f32_e32 v102, v70
	v_add_f32_e32 v64, v98, v64
	v_exp_f32_e32 v103, v71
	v_add_f32_e32 v64, v99, v64
	v_exp_f32_e32 v104, v72
	v_add_f32_e32 v64, v100, v64
	v_exp_f32_e32 v105, v73
	v_add_f32_e32 v64, v101, v64
	v_exp_f32_e32 v106, v74
	v_add_f32_e32 v64, v102, v64
	v_exp_f32_e32 v107, v75
	v_add_f32_e32 v64, v103, v64
	v_exp_f32_e32 v108, v76
	v_add_f32_e32 v64, v104, v64
	v_exp_f32_e32 v109, v77
	v_add_f32_e32 v64, v105, v64
	v_exp_f32_e32 v110, v78
	v_add_f32_e32 v64, v106, v64
	v_exp_f32_e32 v96, v96
	v_add_f32_e32 v64, v107, v64
	v_add_f32_e32 v64, v108, v64
	v_add_f32_e32 v64, v109, v64
	v_add_f32_e32 v64, v110, v64
	v_add_f32_e32 v64, v96, v64
	v_mov_b32_e32 v65, v64
	s_nop 1
	v_permlane32_swap_b32_e32 v64, v65
	v_cvt_pk_bf16_f32 v66, v79, v80
	v_cvt_pk_bf16_f32 v67, v81, v82
	v_cvt_pk_bf16_f32 v68, v83, v84
	v_cvt_pk_bf16_f32 v69, v85, v86
	v_cvt_pk_bf16_f32 v70, v87, v88
	v_cvt_pk_bf16_f32 v71, v89, v90
	v_cvt_pk_bf16_f32 v72, v91, v92
	v_cvt_pk_bf16_f32 v73, v93, v94
	v_cvt_pk_bf16_f32 v74, v95, v97
	v_cvt_pk_bf16_f32 v75, v98, v99
	v_cvt_pk_bf16_f32 v76, v100, v101
	v_cvt_pk_bf16_f32 v77, v102, v103
	v_cvt_pk_bf16_f32 v78, v104, v105
	v_cvt_pk_bf16_f32 v79, v106, v107
	v_cvt_pk_bf16_f32 v80, v108, v109
	v_cvt_pk_bf16_f32 v81, v110, v96
	s_nop 0
	v_permlane32_swap_b32_e32 v66, v68
	v_permlane32_swap_b32_e32 v67, v69
	v_permlane32_swap_b32_e32 v70, v72
	v_permlane32_swap_b32_e32 v71, v73
	v_permlane32_swap_b32_e32 v74, v76
	v_permlane32_swap_b32_e32 v75, v77
	v_permlane32_swap_b32_e32 v78, v80
	v_permlane32_swap_b32_e32 v79, v81
	ds_read_b64_tr_b16 v[82:83], v183 offset:0
	ds_read_b64_tr_b16 v[84:85], v183 offset:0x800
	ds_read_b64_tr_b16 v[86:87], v183 offset:0x1000
	ds_read_b64_tr_b16 v[88:89], v183 offset:0x1800
	ds_read_b64_tr_b16 v[90:91], v183 offset:0x2000
	ds_read_b64_tr_b16 v[92:93], v183 offset:0x2800
	ds_read_b64_tr_b16 v[94:95], v183 offset:0x3000
	ds_read_b64_tr_b16 v[96:97], v183 offset:0x3800
	ds_read_b64_tr_b16 v[98:99], v183 offset:0x200
	ds_read_b64_tr_b16 v[100:101], v183 offset:0xa00
	ds_read_b64_tr_b16 v[102:103], v183 offset:0x1200
	ds_read_b64_tr_b16 v[104:105], v183 offset:0x1a00
	ds_read_b64_tr_b16 v[106:107], v183 offset:0x2200
	ds_read_b64_tr_b16 v[108:109], v183 offset:0x2a00
	ds_read_b64_tr_b16 v[116:117], v183 offset:0x3200
	ds_read_b64_tr_b16 v[118:119], v183 offset:0x3a00
	s_waitcnt lgkmcnt(8)
; #define SBAR() __builtin_amdgcn_sched_barrier(0)
; __device__ __forceinline__ int crow(int r, int hi) { return (r & 3) + 8 * (r >> 2) + 4 * hi; }
; __device__ __forceinline__ unsigned cvtpk(float lo, float hi) { unsigned r; asm volatile("v_cvt_pk_bf16_f32 %0, %1, %2" : "=v"(r) : "v"(lo), "v"(hi)); return r; }
; #define RD8(S, d0) do { constexpr int b_ = v_rd_off(d0, 0, 0); TRRD(S##l0, b_); TRRD(S##h0, b_ + 2048); TRRD(S##l1, b_ + 4096); TRRD(S##h1, b_ + 6144); \
;         TRRD(S##l2, b_ + 8192); TRRD(S##h2, b_ + 10240); TRRD(S##l3, b_ + 12288); TRRD(S##h3, b_ + 14336); } while (0)
; #define RD8(S, d0) do { constexpr int b_ = v_rd_off(d0, 0, 0); TRRD(S##l0, b_); TRRD(S##h0, b_ + 2048); TRRD(S##l1, b_ + 4096); TRRD(S##h1, b_ + 6144); \
;         TRRD(S##l2, b_ + 8192); TRRD(S##h2, b_ + 10240); TRRD(S##l3, b_ + 12288); TRRD(S##h3, b_ + 14336); } while (0)
; __device__ __forceinline__ int crow(int r, int hi) { return (r & 3) + 8 * (r >> 2) + 4 * hi; }
; __device__ __forceinline__ void pv_tile(f32x16* o, int vb, bf16x8 pa0, bf16x8 pa1, bf16x8 pa2, bf16x8 pa3) {
;     ...
;     RD8(A, 0); RD8(B, 1);
;     asm volatile("s_waitcnt lgkmcnt(8)" ::: "memory"); SBAR(); MM4(A, 0); SBAR();
;     RD8(A, 2);
;     asm volatile("s_waitcnt lgkmcnt(8)" ::: "memory"); SBAR(); MM4(B, 1); SBAR();
;     RD8(B, 3);
;     asm volatile("s_waitcnt lgkmcnt(8)" ::: "memory"); SBAR(); MM4(A, 2); SBAR();
;     asm volatile("s_waitcnt lgkmcnt(0)" ::: "memory"); SBAR(); MM4(B, 3);
; __device__ __forceinline__ void attn_block(const BlockRef& cur, char* lds) {
;     ...
;     if (hi == 0) li_l[r32] = l_reg; asm volatile("s_waitcnt lgkmcnt(0)" ::: "memory");
;     float rli[16];
; #pragma unroll
;     for (int r = 0; r < 16; ++r) rli[r] = __builtin_amdgcn_rcpf(li_l[crow(r, hi)]);
;     bf16* Ow = cur.O + (size_t)(wid * QBLK) * LDO;
; #pragma unroll
;     for (int r = 0; r < 16; ++r) { const int orow = crow(r, hi);
; #pragma unroll
;         for (int d0 = 0; d0 < 4; ++d0) { const float v = o[d0][r] * rli[r];
;             const float vn = __shfl_xor(v, 1);
;             if ((r32 & 1) == 0) *(unsigned*)(Ow + (size_t)orow * LDO + d0 * 32 + r32) = cvtpk(v, vn); } }
	s_nop 0
	v_mfma_f32_32x32x16_bf16 v[32:47], v[66:69], v[82:85], v[32:47]
	v_mfma_f32_32x32x16_bf16 v[32:47], v[70:73], v[86:89], v[32:47]
	v_mfma_f32_32x32x16_bf16 v[32:47], v[74:77], v[90:93], v[32:47]
	v_mfma_f32_32x32x16_bf16 v[32:47], v[78:81], v[94:97], v[32:47]
	ds_read_b64_tr_b16 v[82:83], v183 offset:0x400
	ds_read_b64_tr_b16 v[84:85], v183 offset:0xc00
	ds_read_b64_tr_b16 v[86:87], v183 offset:0x1400
	ds_read_b64_tr_b16 v[88:89], v183 offset:0x1c00
	ds_read_b64_tr_b16 v[90:91], v183 offset:0x2400
	ds_read_b64_tr_b16 v[92:93], v183 offset:0x2c00
	ds_read_b64_tr_b16 v[94:95], v183 offset:0x3400
	ds_read_b64_tr_b16 v[96:97], v183 offset:0x3c00
	s_waitcnt lgkmcnt(8)
	v_mfma_f32_32x32x16_bf16 v[48:63], v[66:69], v[98:101], v[48:63]
	v_mfma_f32_32x32x16_bf16 v[48:63], v[70:73], v[102:105], v[48:63]
	v_mfma_f32_32x32x16_bf16 v[48:63], v[74:77], v[106:109], v[48:63]
	v_mfma_f32_32x32x16_bf16 v[48:63], v[78:81], v[116:119], v[48:63]
	ds_read_b64_tr_b16 v[98:99], v183 offset:0x600
	ds_read_b64_tr_b16 v[100:101], v183 offset:0xe00
	ds_read_b64_tr_b16 v[102:103], v183 offset:0x1600
	ds_read_b64_tr_b16 v[104:105], v183 offset:0x1e00
	ds_read_b64_tr_b16 v[106:107], v183 offset:0x2600
	ds_read_b64_tr_b16 v[108:109], v183 offset:0x2e00
	ds_read_b64_tr_b16 v[116:117], v183 offset:0x3600
	ds_read_b64_tr_b16 v[118:119], v183 offset:0x3e00
	s_waitcnt lgkmcnt(8)
	v_mfma_f32_32x32x16_bf16 v[16:31], v[66:69], v[82:85], v[16:31]
	v_mfma_f32_32x32x16_bf16 v[16:31], v[70:73], v[86:89], v[16:31]
	v_mfma_f32_32x32x16_bf16 v[16:31], v[74:77], v[90:93], v[16:31]
	v_mfma_f32_32x32x16_bf16 v[16:31], v[78:81], v[94:97], v[16:31]
	s_waitcnt lgkmcnt(0)
	v_mfma_f32_32x32x16_bf16 v[0:15], v[66:69], v[98:101], v[0:15]
	v_mfma_f32_32x32x16_bf16 v[0:15], v[70:73], v[102:105], v[0:15]
	v_mfma_f32_32x32x16_bf16 v[0:15], v[74:77], v[106:109], v[0:15]
	v_mfma_f32_32x32x16_bf16 v[0:15], v[78:81], v[116:119], v[0:15]
	s_and_saveexec_b64 s[2:3], s[0:1]
	v_add_f32_e32 v66, v112, v113
	v_fmac_f32_e32 v66, v180, v172
	v_add_f32_e32 v64, v64, v65
	v_fmac_f32_e32 v64, v66, v114
	ds_write_b32 v179, v64
	s_or_b64 exec, exec, s[2:3]
	s_waitcnt lgkmcnt(0)
	ds_read_b128 v[76:79], v178
	ds_read_b128 v[72:75], v178 offset:32
	s_lshl_b32 s0, s78, 19
	v_readlane_b32 s1, v255, 19
	s_add_u32 s0, s1, s0
	s_waitcnt lgkmcnt(1)
	v_rcp_f32_e32 v76, v76
	s_addc_u32 s1, s72, 0
	s_add_u32 s2, s0, s73
	s_addc_u32 s3, s1, 0
	s_ashr_i32 s71, s70, 31
	s_lshl_b64 s[0:1], s[70:71], 11
	v_mul_f32_e32 v32, v32, v76
	ds_read_b128 v[68:71], v178 offset:64
	ds_read_b128 v[64:67], v178 offset:96
	s_add_u32 s2, s2, s0
	s_nop 1
	v_mov_b32_dpp v84, v32 quad_perm:[1,0,3,2] row_mask:0xf bank_mask:0xf
	s_addc_u32 s3, s3, s1
	v_and_b32_e32 v80, 1, v175
	v_lshlrev_b32_e32 v160, 1, v177
	v_cmp_eq_u32_e64 s[0:1], 0, v80
	v_lshl_add_u64 v[80:81], s[2:3], 0, v[160:161]
	v_lshlrev_b32_e32 v160, 13, v176
	v_lshl_add_u64 v[82:83], v[80:81], 0, v[160:161]
	s_mov_b64 s[2:3], 0x400
	v_lshl_add_u64 v[80:81], v[82:83], 0, s[2:3]
	s_and_saveexec_b64 s[2:3], s[0:1]
	s_cbranch_execz .LBB0_747
	s_waitcnt lgkmcnt(0)
	v_cvt_pk_bf16_f32 v32, v32, v84
	global_store_dword v[80:81], v32, off

; __device__ __forceinline__ int crow(int r, int hi) { return (r & 3) + 8 * (r >> 2) + 4 * hi; }
; __device__ __forceinline__ unsigned cvtpk(float lo, float hi) { unsigned r; asm volatile("v_cvt_pk_bf16_f32 %0, %1, %2" : "=v"(r) : "v"(lo), "v"(hi)); return r; }
; __device__ __forceinline__ int crow(int r, int hi) { return (r & 3) + 8 * (r >> 2) + 4 * hi; }
; __device__ __forceinline__ void attn_block(const BlockRef& cur, char* lds) {
;     ...
;     for (int r = 0; r < 16; ++r) { const int orow = crow(r, hi);
; #pragma unroll
;         for (int d0 = 0; d0 < 4; ++d0) { const float v = o[d0][r] * rli[r];
;             const float vn = __shfl_xor(v, 1);
;             if ((r32 & 1) == 0) *(unsigned*)(Ow + (size_t)orow * LDO + d0 * 32 + r32) = cvtpk(v, vn); } }
.LBB0_871:
	s_or_b64 exec, exec, s[2:3]
	v_mul_f32_e32 v0, v15, v0
	s_nop 1
	v_mov_b32_dpp v1, v0 quad_perm:[1,0,3,2] row_mask:0xf bank_mask:0xf
	s_and_saveexec_b64 s[2:3], s[0:1]
	s_cbranch_execz .LBB0_537
	s_waitcnt lgkmcnt(0)
	v_cvt_pk_bf16_f32 v2, v0, v1
	v_add_co_u32_e32 v0, vcc, 0xd000, v80
	s_nop 1
	v_addc_co_u32_e32 v1, vcc, 0, v81, vcc
	global_store_dword v[0:1], v2, off offset:2240
	s_branch .LBB0_537
